# speedup vs baseline: 1.0040x; 1.0001x over previous
; DI unsigned cvtpk(float lo, float hi) { f32x2_t v = {lo, hi}; bf16x2_t b = __builtin_convertvector(v, bf16x2_t); return __builtin_bit_cast(unsigned, b); }
; __global__ void __launch_bounds__(NTHR, 2) mega_fwd(Params P) {
;     ...
; #pragma unroll
;                 for (int o = 1; o < 64; o <<= 1)
; #pragma unroll
;                     for (int k = 0; k < 2; ++k) { sk[k] += __shfl_xor(sk[k], o); sq[k] += __shfl_xor(sq[k], o); }
; #pragma unroll
;                 for (int k = 0; k < 2; ++k) {
;                     if (k == 1 && !has1) break;
;                     const int m = mm[k]; const int pos = pos_of_row(m); const size_t kvr = (size_t)kvrow_of_row(m);
;                     float* ockv; float* okr;
;                     if (m < MP) { ockv = outp + O_CKVP + ((size_t)ll * MP + m) * 256; okr = outp + O_KRP + ((size_t)ll * MP + m) * 32; }
;                     else { ockv = outp + O_CKVS + ((size_t)ll * MS + (m - MP)) * 256; okr = outp + O_KRS + ((size_t)ll * MS + (m - MP)) * 32; }
;                     {
;                         const float rs = 1.f / sqrtf(sk[k] * (1.f / 256.f) + EPS);
;                         const f32x4 o = vk[k] * rs * ((const f32x4*)gkv)[lane];
;                         ((f32x4*)ockv)[lane] = o;
;                         u32x2 w; w.x = cvtpk(o.x, o.y); w.y = cvtpk(o.z, o.w); ((u32x2*)(CKVB + kvr * 256))[lane] = w;
;                     }
;                     {
;                         const float rs = 1.f / sqrtf(sq[k] * (1.f / 384.f) + EPS);
;                         const f32x4 o0 = vq0[k] * rs * ((const f32x4*)gq)[lane];
;                         u32x2 w; w.x = cvtpk(o0.x, o0.y); w.y = cvtpk(o0.z, o0.w); ((u32x2*)(CQ + (size_t)m * 384))[lane] = w;
;                         if (lane < 32) { const f32x4 o1 = vq1[k] * rs * ((const f32x4*)(gq + 256))[lane]; u32x2 w1; w1.x = cvtpk(o1.x, o1.y); w1.y = cvtpk(o1.z, o1.w); ((u32x2*)(CQ + (size_t)m * 384 + 256))[lane] = w1; }
;                     }
;                     if (lane < 16) {
;                         const float2 cs = tabM[(size_t)pos * 16 + lane];
.LBB0_547:
	s_or_b64 exec, exec, s[46:47]
	s_waitcnt vmcnt(3)
	v_mul_f32_e32 v33, v23, v23
	v_mul_f32_e32 v57, v25, v25
	v_fmac_f32_e32 v33, v22, v22
	v_fmac_f32_e32 v57, v24, v24
	v_add_f32_e32 v33, v33, v57
	s_waitcnt vmcnt(2)
	v_mul_f32_e32 v57, v19, v19
	v_mul_f32_e32 v59, v21, v21
	v_fmac_f32_e32 v57, v18, v18
	v_fmac_f32_e32 v59, v20, v20
	v_add_f32_e32 v57, v57, v59
	v_mul_f32_e32 v59, v15, v15
	v_fmac_f32_e32 v59, v14, v14
	v_add_f32_e32 v57, v59, v57
	v_mul_f32_e32 v59, v17, v17
	v_fmac_f32_e32 v59, v16, v16
	v_add_f32_e32 v57, v59, v57
	s_waitcnt vmcnt(1)
	v_mul_f32_e32 v59, v11, v11
	v_mul_f32_e32 v65, v13, v13
	v_fmac_f32_e32 v59, v10, v10
	v_fmac_f32_e32 v65, v12, v12
	v_add_f32_e32 v59, v59, v65
	s_waitcnt vmcnt(0)
	v_mul_f32_e32 v65, v7, v7
	s_waitcnt lgkmcnt(1)
	v_mul_f32_e32 v67, v9, v9
	v_fmac_f32_e32 v65, v6, v6
	v_fmac_f32_e32 v67, v8, v8
	v_add_f32_e32 v65, v65, v67
	v_mul_f32_e32 v67, v3, v3
	v_fmac_f32_e32 v67, v2, v2
	v_add_f32_e32 v65, v67, v65
	v_mul_f32_e32 v67, v5, v5
	v_fmac_f32_e32 v67, v4, v4
	v_add_f32_e32 v65, v67, v65
	ds_bpermute_b32 v67, v29, v33
	ds_bpermute_b32 v68, v29, v57
	ds_bpermute_b32 v69, v29, v59
	ds_bpermute_b32 v70, v29, v65
	s_mov_b32 s4, 0x8000
	s_waitcnt lgkmcnt(3)
	v_add_f32_e32 v33, v33, v67
	s_waitcnt lgkmcnt(2)
	v_add_f32_e32 v57, v57, v68
	s_waitcnt lgkmcnt(1)
	v_add_f32_e32 v59, v59, v69
	s_waitcnt lgkmcnt(0)
	v_add_f32_e32 v65, v65, v70
	ds_bpermute_b32 v67, v76, v33
	ds_bpermute_b32 v68, v76, v57
	ds_bpermute_b32 v69, v76, v59
	ds_bpermute_b32 v70, v76, v65
	v_cmp_gt_i32_e64 s[46:47], s4, v26
	v_cmp_gt_i32_e64 s[100:101], s4, v58
	v_and_b32_e32 v116, 0x1fff, v26
	v_and_b32_e32 v117, 63, v26
	v_or_b32_e32 v117, 0x1000, v117
	v_cndmask_b32_e64 v116, v117, v116, s[46:47]
	v_lshl_or_b32 v116, v116, 7, v32
	global_load_dwordx2 v[116:117], v116, s[56:57]
	v_and_b32_e32 v118, 0x1fff, v58
	v_and_b32_e32 v119, 63, v58
	v_or_b32_e32 v119, 0x1000, v119
	v_cndmask_b32_e64 v118, v119, v118, s[100:101]
	v_lshl_or_b32 v118, v118, 7, v32
	global_load_dwordx2 v[118:119], v118, s[56:57]
	s_waitcnt lgkmcnt(3)
	v_add_f32_e32 v33, v33, v67
	s_waitcnt lgkmcnt(2)
	v_add_f32_e32 v57, v57, v68
	s_waitcnt lgkmcnt(1)
	v_add_f32_e32 v59, v59, v69
	s_waitcnt lgkmcnt(0)
	v_add_f32_e32 v65, v65, v70
	ds_bpermute_b32 v67, v77, v33
	ds_bpermute_b32 v68, v77, v57
	ds_bpermute_b32 v69, v77, v59
	ds_bpermute_b32 v70, v77, v65
	v_cmp_lt_i32_e32 vcc, s9, v26
	s_waitcnt lgkmcnt(3)
	v_add_f32_e32 v33, v33, v67
	s_waitcnt lgkmcnt(2)
	v_add_f32_e32 v57, v57, v68
	s_waitcnt lgkmcnt(1)
	v_add_f32_e32 v59, v59, v69
	s_waitcnt lgkmcnt(0)
	v_add_f32_e32 v65, v65, v70
	ds_bpermute_b32 v67, v78, v33
	ds_bpermute_b32 v68, v78, v57
	ds_bpermute_b32 v69, v78, v59
	ds_bpermute_b32 v70, v78, v65
	v_add_u32_e32 v72, 0xffff8000, v26
	s_waitcnt lgkmcnt(3)
	v_add_f32_e32 v33, v33, v67
	s_waitcnt lgkmcnt(2)
	v_add_f32_e32 v57, v57, v68
	s_waitcnt lgkmcnt(1)
	v_add_f32_e32 v59, v59, v69
	s_waitcnt lgkmcnt(0)
	v_add_f32_e32 v67, v65, v70
	ds_bpermute_b32 v65, v79, v33
	ds_bpermute_b32 v68, v79, v57
	ds_bpermute_b32 v69, v79, v59
	ds_bpermute_b32 v70, v79, v67
	s_waitcnt lgkmcnt(3)
	v_add_f32_e32 v65, v33, v65
	s_waitcnt lgkmcnt(2)
	v_add_f32_e32 v82, v57, v68
	s_waitcnt lgkmcnt(1)
	v_add_f32_e32 v33, v59, v69
	s_waitcnt lgkmcnt(0)
	v_add_f32_e32 v57, v67, v70
	ds_bpermute_b32 v83, v80, v65
	ds_bpermute_b32 v84, v80, v82
	ds_bpermute_b32 v67, v80, v33
	ds_bpermute_b32 v81, v80, v57
	v_and_b32_e32 v59, 63, v26
	v_mov_b64_e32 v[68:69], v[26:27]
	s_and_saveexec_b64 s[48:49], vcc
	v_lshrrev_b32_e32 v68, 6, v72
	s_movk_i32 s4, 0x1040
	v_mul_lo_u32 v68, v68, s4
	v_or_b32_e32 v68, v68, v59
	v_add_u32_e32 v68, 0x9000, v68
	v_mov_b32_e32 v69, v0
	s_or_b64 exec, exec, s[48:49]
	s_and_saveexec_b64 s[4:5], vcc
	s_xor_b64 s[48:49], exec, s[4:5]
	v_mov_b32_e32 v73, v0
	v_lshl_add_u64 v[70:71], s[58:59], 0, v[72:73]
	s_or_saveexec_b64 s[48:49], s[48:49]
	v_mov_b64_e32 v[72:73], 0xd000000
	v_mov_b64_e32 v[74:75], 0xcf00000
	s_xor_b64 exec, exec, s[48:49]
	v_lshl_add_u64 v[70:71], s[60:61], 0, v[26:27]
	v_mov_b64_e32 v[72:73], 0xc200000
	v_mov_b64_e32 v[74:75], 0x8200000
	s_or_b64 exec, exec, s[48:49]
	s_waitcnt lgkmcnt(3)
; DI unsigned cvtpk(float lo, float hi) { f32x2_t v = {lo, hi}; bf16x2_t b = __builtin_convertvector(v, bf16x2_t); return __builtin_bit_cast(unsigned, b); }
; __global__ void __launch_bounds__(NTHR, 2) mega_fwd(Params P) {
;     ...
;                     {
;                         const float rs = 1.f / sqrtf(sk[k] * (1.f / 256.f) + EPS);
;                         const f32x4 o = vk[k] * rs * ((const f32x4*)gkv)[lane];
;                         ((f32x4*)ockv)[lane] = o;
;                         u32x2 w; w.x = cvtpk(o.x, o.y); w.y = cvtpk(o.z, o.w); ((u32x2*)(CKVB + kvr * 256))[lane] = w;
;                     }
;                     {
;                         const float rs = 1.f / sqrtf(sq[k] * (1.f / 384.f) + EPS);
;                         const f32x4 o0 = vq0[k] * rs * ((const f32x4*)gq)[lane];
;                         u32x2 w; w.x = cvtpk(o0.x, o0.y); w.y = cvtpk(o0.z, o0.w); ((u32x2*)(CQ + (size_t)m * 384))[lane] = w;
;                         if (lane < 32) { const f32x4 o1 = vq1[k] * rs * ((const f32x4*)(gq + 256))[lane]; u32x2 w1; w1.x = cvtpk(o1.x, o1.y); w1.y = cvtpk(o1.z, o1.w); ((u32x2*)(CQ + (size_t)m * 384 + 256))[lane] = w1; }
;                     }
	v_add_f32_e32 v65, v65, v83
	s_waitcnt lgkmcnt(2)
	v_add_f32_e32 v86, v82, v84
	v_lshl_add_u64 v[74:75], s[52:53], 0, v[74:75]
	v_lshlrev_b64 v[82:83], 10, v[70:71]
	v_fmamk_f32 v65, v65, 0x3b800000, v214
	s_mov_b32 s6, 0xf800000
	v_lshl_add_u64 v[74:75], v[74:75], 0, v[82:83]
	v_cmp_gt_f32_e32 vcc, s6, v65
	v_mul_f32_e32 v82, 0x4f800000, v65
	s_nop 0
	v_cndmask_b32_e32 v65, v65, v82, vcc
	v_sqrt_f32_e32 v82, v65
	s_nop 0
	v_add_u32_e32 v83, -1, v82
	v_fma_f32 v84, -v83, v82, v65
	v_cmp_ge_f32_e64 s[48:49], 0, v84
	v_add_u32_e32 v84, 1, v82
	s_nop 0
	v_cndmask_b32_e64 v83, v82, v83, s[48:49]
	v_fma_f32 v82, -v84, v82, v65
	v_cmp_lt_f32_e64 s[48:49], 0, v82
	s_nop 1
	v_cndmask_b32_e64 v82, v83, v84, s[48:49]
	v_mul_f32_e32 v83, 0x37800000, v82
	v_cndmask_b32_e32 v82, v82, v83, vcc
	v_cmp_class_f32_e32 vcc, v65, v215
	s_nop 1
	v_cndmask_b32_e32 v65, v82, v65, vcc
	v_div_scale_f32 v82, s[4:5], v65, v65, 1.0
	v_rcp_f32_e32 v83, v82
	s_nop 0
	v_fma_f32 v84, -v82, v83, 1.0
	v_fmac_f32_e32 v83, v84, v83
	v_div_scale_f32 v84, vcc, 1.0, v65, 1.0
	v_mul_f32_e32 v85, v84, v83
	v_fma_f32 v87, -v82, v85, v84
	v_fmac_f32_e32 v85, v87, v83
	v_fma_f32 v82, -v82, v85, v84
	v_div_fmas_f32 v82, v82, v83, v85
	v_div_fixup_f32 v82, v82, v65, 1.0
	v_pk_mul_f32 v[84:85], v[22:23], v[82:83] op_sel_hi:[1,0]
	v_pk_mul_f32 v[82:83], v[24:25], v[82:83] op_sel_hi:[1,0]
	v_mov_b32_e32 v65, v0
	v_lshl_add_u64 v[74:75], v[74:75], 0, v[64:65]
	s_waitcnt vmcnt(0)
	v_pk_mul_f32 v[24:25], v[82:83], v[102:103]
	v_pk_mul_f32 v[22:23], v[84:85], v[100:101]
	global_store_dwordx4 v[74:75], v[22:25], off
	s_nop 1
	v_cvt_pk_bf16_f32 v22, v22, v23
	v_cvt_pk_bf16_f32 v23, v24, v25
	v_lshlrev_b64 v[24:25], 9, v[68:69]
	v_lshl_add_u64 v[24:25], v[34:35], 0, v[24:25]
	global_store_dwordx2 v[24:25], v[22:23], off
	v_fmamk_f32 v22, v86, 0x3b2aaaab, v214
	v_cmp_gt_f32_e32 vcc, s6, v22
	v_mul_f32_e32 v23, 0x4f800000, v22
	s_nop 0
	v_cndmask_b32_e32 v22, v22, v23, vcc
	v_sqrt_f32_e32 v23, v22
	s_nop 0
	v_add_u32_e32 v24, -1, v23
	v_fma_f32 v25, -v24, v23, v22
	v_cmp_ge_f32_e64 s[48:49], 0, v25
	v_add_u32_e32 v25, 1, v23
	s_nop 0
	v_cndmask_b32_e64 v24, v23, v24, s[48:49]
	v_fma_f32 v23, -v25, v23, v22
	v_cmp_lt_f32_e64 s[48:49], 0, v23
	s_nop 1
	v_cndmask_b32_e64 v23, v24, v25, s[48:49]
	v_mul_f32_e32 v24, 0x37800000, v23
	v_cndmask_b32_e32 v23, v23, v24, vcc
	v_cmp_class_f32_e32 vcc, v22, v215
	s_nop 1
	v_cndmask_b32_e32 v22, v23, v22, vcc
	v_div_scale_f32 v23, s[4:5], v22, v22, 1.0
	v_rcp_f32_e32 v24, v23
	s_nop 0
	v_fma_f32 v25, -v23, v24, 1.0
	v_fmac_f32_e32 v24, v25, v24
	v_div_scale_f32 v25, vcc, 1.0, v22, 1.0
	v_mul_f32_e32 v65, v25, v24
	v_fma_f32 v74, -v23, v65, v25
	v_fmac_f32_e32 v65, v74, v24
	v_fma_f32 v23, -v23, v65, v25
	v_div_fmas_f32 v23, v23, v24, v65
	v_div_fixup_f32 v22, v23, v22, 1.0
	v_pk_mul_f32 v[24:25], v[18:19], v[22:23] op_sel_hi:[1,0]
	v_pk_mul_f32 v[74:75], v[20:21], v[22:23] op_sel_hi:[1,0]
	v_pk_mul_f32 v[18:19], v[24:25], v[104:105]
	v_pk_mul_f32 v[20:21], v[74:75], v[106:107]
	v_cvt_pk_bf16_f32 v24, v18, v19
	v_lshl_add_u64 v[18:19], s[54:55], 0, v[46:47]
	v_cvt_pk_bf16_f32 v25, v20, v21
	v_add_co_u32_e32 v20, vcc, 0x18600000, v18
	s_nop 1
	v_addc_co_u32_e32 v21, vcc, 0, v19, vcc
	global_store_dwordx2 v[20:21], v[24:25], off
	s_and_saveexec_b64 s[48:49], s[40:41]
	s_cbranch_execz .LBB0_557
	v_mov_b32_e32 v23, v22
	v_mov_b32_e32 v20, v22
	v_mov_b32_e32 v21, v22
	v_pk_mul_f32 v[20:21], v[16:17], v[20:21]
	v_pk_mul_f32 v[22:23], v[14:15], v[22:23]
	v_pk_mul_f32 v[16:17], v[20:21], v[110:111]
	v_pk_mul_f32 v[14:15], v[22:23], v[108:109]
	s_nop 0
	v_cvt_pk_bf16_f32 v14, v14, v15
	v_cvt_pk_bf16_f32 v15, v16, v17
	v_add_co_u32_e32 v16, vcc, 0x18600000, v18
	s_nop 1
	v_addc_co_u32_e32 v17, vcc, 0, v19, vcc
	global_store_dwordx2 v[16:17], v[14:15], off offset:512
	s_or_b64 exec, exec, s[48:49]
	s_and_saveexec_b64 s[4:5], s[42:43]
	s_xor_b64 s[48:49], exec, s[4:5]
	s_cbranch_execnz .LBB0_558

; DI unsigned short f2bf(float f) { return (unsigned short)(cvtpk(f, 0.f) & 0xffffu); }
; __global__ void __launch_bounds__(NTHR, 2) mega_fwd(Params P) {
;     ...
;                     if (lane < 16) {
;                         const float2 cs = tabM[(size_t)pos * 16 + lane];
;                         const float o1 = x1[k] * cs.x - x2[k] * cs.y, o2 = x2[k] * cs.x + x1[k] * cs.y;
;                         okr[lane] = o1; okr[16 + lane] = o2;
;                         KR[kvr * 32 + lane] = f2bf(o1); KR[kvr * 32 + 16 + lane] = f2bf(o2);
.LBB0_556:
	v_lshl_add_u64 v[14:15], s[52:53], 0, v[72:73]
	v_lshlrev_b64 v[16:17], 7, v[70:71]
	v_lshl_add_u64 v[14:15], v[14:15], 0, v[16:17]
	v_and_b32_e32 v16, 0x1fff, v26
	v_or_b32_e32 v17, 0x1000, v59
	v_cndmask_b32_e64 v16, v17, v16, s[46:47]
	v_lshl_or_b32 v16, v16, 7, v32
	v_mov_b32_e32 v16, v116
	v_mov_b32_e32 v17, v117
	v_mul_f32_e32 v18, v60, v17
	v_mul_f32_e32 v19, v62, v17
	v_fma_f32 v18, v62, v16, -v18
	v_fmac_f32_e32 v19, v60, v16
	v_lshlrev_b32_e32 v16, 2, v28
	v_mov_b32_e32 v17, v0
	v_lshl_add_u64 v[14:15], v[14:15], 0, v[16:17]
	global_store_dword v[14:15], v18, off
	global_store_dword v[14:15], v19, off offset:64
	v_lshlrev_b64 v[14:15], 6, v[68:69]
	v_cvt_pk_bf16_f32 v16, v18, s0
	v_lshl_add_u64 v[14:15], v[40:41], 0, v[14:15]
	global_store_short v[14:15], v16, off
	v_cvt_pk_bf16_f32 v16, v19, s0
	global_store_short v[14:15], v16, off offset:32
	s_or_b64 exec, exec, s[48:49]
	s_and_saveexec_b64 s[48:49], s[44:45]
	s_cbranch_execz .LBB0_530
	s_branch .LBB0_562

; DI unsigned short f2bf(float f) { return (unsigned short)(cvtpk(f, 0.f) & 0xffffu); }
; __global__ void __launch_bounds__(NTHR, 2) mega_fwd(Params P) {
;     ...
;                     if (lane < 16) {
;                         const float2 cs = tabM[(size_t)pos * 16 + lane];
;                         const float o1 = x1[k] * cs.x - x2[k] * cs.y, o2 = x2[k] * cs.x + x1[k] * cs.y;
;                         okr[lane] = o1; okr[16 + lane] = o2;
;                         KR[kvr * 32 + lane] = f2bf(o1); KR[kvr * 32 + 16 + lane] = f2bf(o2);
.LBB0_575:
	v_lshl_add_u64 v[2:3], s[52:53], 0, v[18:19]
	v_lshlrev_b64 v[4:5], 7, v[16:17]
	v_lshl_add_u64 v[2:3], v[2:3], 0, v[4:5]
	v_and_b32_e32 v1, 0x1fff, v56
	v_or_b32_e32 v4, 0x1000, v22
	v_cndmask_b32_e64 v1, v4, v1, s[44:45]
	v_lshl_or_b32 v1, v1, 7, v32
	v_mov_b32_e32 v4, v118
	v_mov_b32_e32 v5, v119
	v_mul_f32_e32 v1, v63, v5
	v_mul_f32_e32 v6, v61, v5
	v_fma_f32 v1, v61, v4, -v1
	v_fmac_f32_e32 v6, v63, v4
	v_lshlrev_b32_e32 v4, 2, v28
	v_mov_b32_e32 v5, v0
	v_lshl_add_u64 v[2:3], v[2:3], 0, v[4:5]
	global_store_dword v[2:3], v1, off
	global_store_dword v[2:3], v6, off offset:64
	v_lshlrev_b64 v[2:3], 6, v[14:15]
	v_cvt_pk_bf16_f32 v1, v1, s0
	v_lshl_add_u64 v[2:3], v[40:41], 0, v[2:3]
	global_store_short v[2:3], v1, off
	v_cvt_pk_bf16_f32 v1, v6, s0
	global_store_short v[2:3], v1, off offset:32
	s_branch .LBB0_530
